# speedup vs baseline: 1.0087x; 1.0087x over previous
.LBB0_117:
	s_or_b64 exec, exec, s[46:47]
	s_lshr_b32 s46, s42, 3
	s_ashr_i32 s43, s42, 31
	s_lshl_b64 s[44:45], s[42:43], 12
	s_and_b32 s43, s46, 3
	s_lshl_b32 s46, s43, 14
	s_lshl_b32 s47, s43, 9
	s_lshl_b32 s43, s43, 8
	s_lshl_b64 s[28:29], s[28:29], 2
	s_add_u32 s28, s33, s28
	s_addc_u32 s29, s50, s29
	s_lshl_b32 s48, s51, 2
	s_add_u32 s28, s28, s48
	s_addc_u32 s29, s29, 0
	s_add_u32 s28, s28, s40
	s_addc_u32 s29, s29, s41
	global_load_dwordx4 v[42:45], v99, s[28:29]
	s_lshl_b64 s[28:29], s[26:27], 22
	s_or_b32 s28, s28, s46
	v_lshl_add_u64 v[10:11], v[60:61], 0, s[44:45]
	v_lshl_add_u64 v[84:85], s[28:29], 0, v[70:71]
	s_lshl_b64 s[28:29], s[26:27], 17
	v_lshlrev_b64 v[82:83], 6, v[10:11]
	s_or_b32 s28, s28, s47
	v_mov_b32_e32 v10, 0x1800000
	v_lshl_add_u64 v[86:87], s[28:29], 0, v[72:73]
	s_mul_i32 s46, s26, 0x1800000
	v_mad_i64_i32 v[10:11], s[28:29], s26, v10, v[74:75]
	v_lshl_add_u64 v[6:7], v[8:9], 0, v[6:7]
	s_mul_hi_i32 s27, s26, 0x1800000
	v_lshl_add_u64 v[88:89], v[6:7], 1, v[10:11]
	s_or_b32 s26, s46, s43
	v_mov_b32_e32 v10, 0
	v_lshl_add_u64 v[90:91], s[26:27], 0, v[76:77]
	s_mov_b32 s43, 63
	v_mov_b32_e32 v11, v10
	v_mov_b32_e32 v12, v10
	v_mov_b32_e32 v13, v10
	v_mov_b32_e32 v14, v10
	v_mov_b32_e32 v15, v10
	v_mov_b32_e32 v16, v10
	v_mov_b32_e32 v17, v10
	s_cmp_eq_u64 s[6:7], 0
	s_cbranch_scc0 .Lscan_prio_skip
	s_setprio 2
.Lscan_prio_skip:
	s_waitcnt vmcnt(0)
.LBB0_118:
	ds_write_b128 v1, v[18:21]
	ds_write_b128 v1, v[30:33] offset:8704
	ds_write_b128 v1, v[22:25] offset:17408
	ds_write_b128 v1, v[26:29] offset:26112
	ds_write_b128 v57, v[34:37] offset:34816
	ds_write_b128 v57, v[38:41] offset:44032
	s_and_saveexec_b64 s[26:27], s[6:7]
	s_cbranch_execz .LBB0_120
	v_add_u32_e32 v6, v63, v95
	ds_write_b16 v6, v2 offset:53248
	ds_write_b16_d16_hi v6, v2 offset:53392
	ds_write_b16 v6, v3 offset:53536
	ds_write_b16_d16_hi v6, v3 offset:53680
	ds_write_b16 v6, v4 offset:53824
	ds_write_b16_d16_hi v6, v4 offset:53968
	ds_write_b16 v6, v5 offset:54112
	ds_write_b16_d16_hi v6, v5 offset:54256

.LBB0_134:
	s_setprio 0
	s_mov_b64 s[2:3], 0
